# B-fragment (MFMA SrcA) register tuples re-allocated to 2-mod-4 alignment in P7/P15 K-loops
# speedup vs baseline: 1.0106x; 1.0011x over previous
.LBB0_1171:
	s_add_i32 s36, s36, 1
	s_mov_b32 s52, s6
	s_lshl_b32 s6, s36, 5
	s_add_i32 s6, s6, s3
	s_mov_b64 s[22:23], s[8:9]
	s_lshl_b32 s8, s6, 3
	s_ashr_i32 s7, s6, 2
	s_add_i32 s8, s8, s39
	s_cmpk_lt_i32 s6, 0x158
	s_cselect_b32 s6, s7, s8
	s_mov_b32 s53, s26
	s_cselect_b32 s26, s40, 32
	s_cmpk_lt_i32 s6, 0x56
	s_cselect_b64 s[18:19], -1, 0
	s_lshl_b32 s7, s26, 21
	v_readlane_b32 s0, v250, 46
	s_mov_b64 s[20:21], s[10:11]
	v_readlane_b32 s1, v250, 47
	s_add_u32 s10, s0, s7
	s_addc_u32 s11, s1, 0
	s_and_b64 s[8:9], s[18:19], exec
	s_cselect_b32 s54, s11, s21
	s_cselect_b32 s55, s10, s20
	s_ashr_i32 s7, s6, 31
	s_lshl_b64 s[8:9], s[6:7], 21
	s_add_u32 s8, s27, s8
	s_addc_u32 s9, s30, s9
	s_and_b64 s[24:25], s[18:19], exec
	s_cselect_b32 s7, s9, s23
	s_cselect_b32 s56, s8, s22
	s_add_u32 s20, s20, 0x100080
	s_addc_u32 s21, s21, 0
	s_add_u32 s57, s22, 0x100
	s_addc_u32 s60, s23, 0
	s_mov_b32 s61, -2
	s_waitcnt lgkmcnt(0)
	s_add_u32 s62, s20, 0xfff00000
	s_addc_u32 s63, s21, -1
	s_mov_b32 m0, s37
	ds_read_b128 v[142:145], v148
	global_load_lds_dwordx4 v130, s[62:63]
	s_mov_b32 m0, s38
	ds_read_b128 v[154:157], v148 offset:1024
	global_load_lds_dwordx4 v134, s[62:63]
	s_mov_b32 m0, s42
	ds_read_b128 v[158:161], v148 offset:2048
	global_load_lds_dwordx4 v138, s[20:21]
	s_mov_b32 m0, s43
	ds_read_b128 v[170:173], v148 offset:3072
	global_load_lds_dwordx4 v140, s[20:21]
	ds_read_b128 v[178:181], v149
	ds_read_b128 v[182:185], v149 offset:1024
	ds_read_b128 v[186:189], v149 offset:2048
	ds_read_b128 v[230:233], v149 offset:3072
	s_add_u32 s22, s20, 0xfff00080
	s_addc_u32 s23, s21, -1
	s_cmp_eq_u32 s61, 60
	s_cselect_b32 s25, s54, s23
	s_cselect_b32 s24, s55, s22
	s_cselect_b32 s23, s7, s60
	s_cselect_b32 s22, s56, s57
	ds_read_b128 v[192:195], v150
	ds_read_b128 v[202:205], v150 offset:1024
	ds_read_b128 v[206:209], v150 offset:2048
	ds_read_b128 v[210:213], v150 offset:3072
	ds_read_b128 v[214:217], v150 offset:4096
	ds_read_b128 v[218:221], v150 offset:5120
	ds_read_b128 v[222:225], v150 offset:6144
	ds_read_b128 v[226:229], v150 offset:7168
	s_waitcnt vmcnt(8)
	s_waitcnt lgkmcnt(0)
	s_barrier
	v_mfma_f32_16x16x32_bf16 v[126:129], v[142:145], v[192:195], 0
	v_mfma_f32_16x16x32_bf16 v[126:129], v[154:157], v[202:205], v[126:129]
	v_mfma_f32_16x16x32_bf16 v[118:121], v[170:173], v[202:205], 0
	v_mfma_f32_16x16x32_bf16 v[118:121], v[158:161], v[192:195], v[118:121]
	v_mfma_f32_16x16x32_bf16 v[102:105], v[158:161], v[206:209], 0
	v_mfma_f32_16x16x32_bf16 v[102:105], v[170:173], v[210:213], v[102:105]
	v_mfma_f32_16x16x32_bf16 v[110:113], v[154:157], v[210:213], 0
	v_mfma_f32_16x16x32_bf16 v[110:113], v[142:145], v[206:209], v[110:113]
	v_mfma_f32_16x16x32_bf16 v[94:97], v[142:145], v[214:217], 0
	v_mfma_f32_16x16x32_bf16 v[94:97], v[154:157], v[218:221], v[94:97]
	v_mfma_f32_16x16x32_bf16 v[86:89], v[170:173], v[218:221], 0
	v_mfma_f32_16x16x32_bf16 v[86:89], v[158:161], v[214:217], v[86:89]
	v_mfma_f32_16x16x32_bf16 v[70:73], v[158:161], v[222:225], 0
	v_mfma_f32_16x16x32_bf16 v[70:73], v[170:173], v[226:229], v[70:73]
	v_mfma_f32_16x16x32_bf16 v[78:81], v[154:157], v[226:229], 0
	v_mfma_f32_16x16x32_bf16 v[78:81], v[142:145], v[222:225], v[78:81]
	v_mfma_f32_16x16x32_bf16 v[74:77], v[178:181], v[222:225], 0
	v_mfma_f32_16x16x32_bf16 v[74:77], v[182:185], v[226:229], v[74:77]
	v_mfma_f32_16x16x32_bf16 v[66:69], v[230:233], v[226:229], 0
	v_mfma_f32_16x16x32_bf16 v[66:69], v[186:189], v[222:225], v[66:69]
	v_mfma_f32_16x16x32_bf16 v[82:85], v[186:189], v[214:217], 0
	v_mfma_f32_16x16x32_bf16 v[82:85], v[230:233], v[218:221], v[82:85]
	v_mfma_f32_16x16x32_bf16 v[90:93], v[182:185], v[218:221], 0
	v_mfma_f32_16x16x32_bf16 v[90:93], v[178:181], v[214:217], v[90:93]
	v_mfma_f32_16x16x32_bf16 v[106:109], v[178:181], v[206:209], 0
	v_mfma_f32_16x16x32_bf16 v[106:109], v[182:185], v[210:213], v[106:109]
	v_mfma_f32_16x16x32_bf16 v[98:101], v[230:233], v[210:213], 0
	v_mfma_f32_16x16x32_bf16 v[98:101], v[186:189], v[206:209], v[98:101]
	v_mfma_f32_16x16x32_bf16 v[114:117], v[186:189], v[192:195], 0
	v_mfma_f32_16x16x32_bf16 v[114:117], v[230:233], v[202:205], v[114:117]
	v_mfma_f32_16x16x32_bf16 v[122:125], v[182:185], v[202:205], 0
	v_mfma_f32_16x16x32_bf16 v[122:125], v[178:181], v[192:195], v[122:125]
	s_barrier
	s_mov_b32 m0, s44
	s_add_u32 s62, s22, 0x100000
	global_load_lds_dwordx4 v132, s[22:23]
	s_mov_b32 m0, s45
	s_addc_u32 s63, s23, 0
	global_load_lds_dwordx4 v136, s[22:23]
	s_mov_b32 m0, s46
	ds_read_b128 v[192:195], v150 offset:16384
	global_load_lds_dwordx4 v132, s[62:63]
	s_mov_b32 m0, s47
	ds_read_b128 v[202:205], v150 offset:17408
	global_load_lds_dwordx4 v136, s[62:63]
	ds_read_b128 v[206:209], v150 offset:18432
	ds_read_b128 v[210:213], v150 offset:19456
	ds_read_b128 v[214:217], v150 offset:20480
	ds_read_b128 v[218:221], v150 offset:21504
	ds_read_b128 v[222:225], v150 offset:22528
	ds_read_b128 v[226:229], v150 offset:23552
	s_waitcnt vmcnt(6)
	s_waitcnt lgkmcnt(0)
	s_barrier
	v_mfma_f32_16x16x32_bf16 v[62:65], v[142:145], v[192:195], 0
	v_mfma_f32_16x16x32_bf16 v[62:65], v[154:157], v[202:205], v[62:65]
	v_mfma_f32_16x16x32_bf16 v[54:57], v[170:173], v[202:205], 0
	v_mfma_f32_16x16x32_bf16 v[54:57], v[158:161], v[192:195], v[54:57]
	v_mfma_f32_16x16x32_bf16 v[38:41], v[158:161], v[206:209], 0
	v_mfma_f32_16x16x32_bf16 v[38:41], v[170:173], v[210:213], v[38:41]
	v_mfma_f32_16x16x32_bf16 v[46:49], v[154:157], v[210:213], 0
	v_mfma_f32_16x16x32_bf16 v[46:49], v[142:145], v[206:209], v[46:49]
	v_mfma_f32_16x16x32_bf16 v[30:33], v[142:145], v[214:217], 0
	v_mfma_f32_16x16x32_bf16 v[30:33], v[154:157], v[218:221], v[30:33]
	v_mfma_f32_16x16x32_bf16 v[22:25], v[170:173], v[218:221], 0
	v_mfma_f32_16x16x32_bf16 v[22:25], v[158:161], v[214:217], v[22:25]
	v_mfma_f32_16x16x32_bf16 v[6:9], v[158:161], v[222:225], 0
	v_mfma_f32_16x16x32_bf16 v[6:9], v[170:173], v[226:229], v[6:9]
	v_mfma_f32_16x16x32_bf16 v[14:17], v[154:157], v[226:229], 0
	v_mfma_f32_16x16x32_bf16 v[14:17], v[142:145], v[222:225], v[14:17]
	v_mfma_f32_16x16x32_bf16 v[10:13], v[178:181], v[222:225], 0
	v_mfma_f32_16x16x32_bf16 v[10:13], v[182:185], v[226:229], v[10:13]
	v_mfma_f32_16x16x32_bf16 v[2:5], v[230:233], v[226:229], 0
	v_mfma_f32_16x16x32_bf16 v[2:5], v[186:189], v[222:225], v[2:5]
	v_mfma_f32_16x16x32_bf16 v[18:21], v[186:189], v[214:217], 0
	v_mfma_f32_16x16x32_bf16 v[18:21], v[230:233], v[218:221], v[18:21]
	v_mfma_f32_16x16x32_bf16 v[26:29], v[182:185], v[218:221], 0
	v_mfma_f32_16x16x32_bf16 v[26:29], v[178:181], v[214:217], v[26:29]
	v_mfma_f32_16x16x32_bf16 v[42:45], v[178:181], v[206:209], 0
	v_mfma_f32_16x16x32_bf16 v[42:45], v[182:185], v[210:213], v[42:45]
	v_mfma_f32_16x16x32_bf16 v[34:37], v[230:233], v[210:213], 0
	v_mfma_f32_16x16x32_bf16 v[34:37], v[186:189], v[206:209], v[34:37]
	v_mfma_f32_16x16x32_bf16 v[50:53], v[186:189], v[192:195], 0
	v_mfma_f32_16x16x32_bf16 v[50:53], v[230:233], v[202:205], v[50:53]
	v_mfma_f32_16x16x32_bf16 v[58:61], v[182:185], v[202:205], 0
	v_mfma_f32_16x16x32_bf16 v[58:61], v[178:181], v[192:195], v[58:61]
	s_barrier
	s_mov_b32 m0, s31
	ds_read_b128 v[142:145], v151
	global_load_lds_dwordx4 v130, s[24:25]
	s_mov_b32 m0, s33
	ds_read_b128 v[154:157], v151 offset:1024
	global_load_lds_dwordx4 v134, s[24:25]
	s_add_u32 s24, s24, 0x100000
	s_addc_u32 s25, s25, 0
	s_mov_b32 m0, s34
	ds_read_b128 v[158:161], v151 offset:2048
	global_load_lds_dwordx4 v130, s[24:25]
	s_mov_b32 m0, s35
	ds_read_b128 v[170:173], v151 offset:3072
	global_load_lds_dwordx4 v134, s[24:25]
	ds_read_b128 v[178:181], v152
	ds_read_b128 v[182:185], v152 offset:1024
	ds_read_b128 v[186:189], v152 offset:2048
	ds_read_b128 v[230:233], v152 offset:3072
	ds_read_b128 v[192:195], v150 offset:32768
	ds_read_b128 v[202:205], v150 offset:33792
	ds_read_b128 v[206:209], v150 offset:34816
	ds_read_b128 v[210:213], v150 offset:35840
	ds_read_b128 v[214:217], v150 offset:36864
	ds_read_b128 v[218:221], v150 offset:37888
	ds_read_b128 v[222:225], v150 offset:38912
	ds_read_b128 v[226:229], v150 offset:39936
	s_waitcnt vmcnt(8)
	s_waitcnt lgkmcnt(0)
	s_barrier
	v_mfma_f32_16x16x32_bf16 v[126:129], v[142:145], v[192:195], v[126:129]
	v_mfma_f32_16x16x32_bf16 v[126:129], v[154:157], v[202:205], v[126:129]
	v_mfma_f32_16x16x32_bf16 v[118:121], v[170:173], v[202:205], v[118:121]
	v_mfma_f32_16x16x32_bf16 v[118:121], v[158:161], v[192:195], v[118:121]
	v_mfma_f32_16x16x32_bf16 v[102:105], v[158:161], v[206:209], v[102:105]
	v_mfma_f32_16x16x32_bf16 v[102:105], v[170:173], v[210:213], v[102:105]
	v_mfma_f32_16x16x32_bf16 v[110:113], v[154:157], v[210:213], v[110:113]
	v_mfma_f32_16x16x32_bf16 v[110:113], v[142:145], v[206:209], v[110:113]
	v_mfma_f32_16x16x32_bf16 v[94:97], v[142:145], v[214:217], v[94:97]
	v_mfma_f32_16x16x32_bf16 v[94:97], v[154:157], v[218:221], v[94:97]
	v_mfma_f32_16x16x32_bf16 v[86:89], v[170:173], v[218:221], v[86:89]
	v_mfma_f32_16x16x32_bf16 v[86:89], v[158:161], v[214:217], v[86:89]
	v_mfma_f32_16x16x32_bf16 v[70:73], v[158:161], v[222:225], v[70:73]
	v_mfma_f32_16x16x32_bf16 v[70:73], v[170:173], v[226:229], v[70:73]
	v_mfma_f32_16x16x32_bf16 v[78:81], v[154:157], v[226:229], v[78:81]
	v_mfma_f32_16x16x32_bf16 v[78:81], v[142:145], v[222:225], v[78:81]
	v_mfma_f32_16x16x32_bf16 v[74:77], v[178:181], v[222:225], v[74:77]
	v_mfma_f32_16x16x32_bf16 v[74:77], v[182:185], v[226:229], v[74:77]
	v_mfma_f32_16x16x32_bf16 v[66:69], v[230:233], v[226:229], v[66:69]
	v_mfma_f32_16x16x32_bf16 v[66:69], v[186:189], v[222:225], v[66:69]
	v_mfma_f32_16x16x32_bf16 v[82:85], v[186:189], v[214:217], v[82:85]
	v_mfma_f32_16x16x32_bf16 v[82:85], v[230:233], v[218:221], v[82:85]
	v_mfma_f32_16x16x32_bf16 v[90:93], v[182:185], v[218:221], v[90:93]
	v_mfma_f32_16x16x32_bf16 v[90:93], v[178:181], v[214:217], v[90:93]
	v_mfma_f32_16x16x32_bf16 v[106:109], v[178:181], v[206:209], v[106:109]
	v_mfma_f32_16x16x32_bf16 v[106:109], v[182:185], v[210:213], v[106:109]
	v_mfma_f32_16x16x32_bf16 v[98:101], v[230:233], v[210:213], v[98:101]
	v_mfma_f32_16x16x32_bf16 v[98:101], v[186:189], v[206:209], v[98:101]
	v_mfma_f32_16x16x32_bf16 v[114:117], v[186:189], v[192:195], v[114:117]
	v_mfma_f32_16x16x32_bf16 v[114:117], v[230:233], v[202:205], v[114:117]
	v_mfma_f32_16x16x32_bf16 v[122:125], v[182:185], v[202:205], v[122:125]
	v_mfma_f32_16x16x32_bf16 v[122:125], v[178:181], v[192:195], v[122:125]
	s_barrier
	s_mov_b32 m0, s48
	s_add_u32 s22, s22, 0x80
	s_addc_u32 s23, s23, 0
	global_load_lds_dwordx4 v132, s[22:23]
	s_mov_b32 m0, s49
	ds_read_b128 v[192:195], v150 offset:49152
	global_load_lds_dwordx4 v136, s[22:23]
	s_mov_b32 m0, s50
	s_add_u32 s22, s22, 0x100000
	s_addc_u32 s23, s23, 0
	global_load_lds_dwordx4 v132, s[22:23]
	s_mov_b32 m0, s51
	ds_read_b128 v[202:205], v150 offset:50176
	global_load_lds_dwordx4 v136, s[22:23]
	ds_read_b128 v[206:209], v150 offset:51200
	ds_read_b128 v[210:213], v150 offset:52224
	ds_read_b128 v[214:217], v150 offset:53248
	ds_read_b128 v[218:221], v150 offset:54272
	ds_read_b128 v[222:225], v150 offset:55296
	ds_read_b128 v[226:229], v150 offset:56320
	s_waitcnt vmcnt(6)
	s_waitcnt lgkmcnt(0)
	s_barrier
	v_mfma_f32_16x16x32_bf16 v[62:65], v[142:145], v[192:195], v[62:65]
	v_mfma_f32_16x16x32_bf16 v[62:65], v[154:157], v[202:205], v[62:65]
	v_mfma_f32_16x16x32_bf16 v[54:57], v[170:173], v[202:205], v[54:57]
	v_mfma_f32_16x16x32_bf16 v[54:57], v[158:161], v[192:195], v[54:57]
	v_mfma_f32_16x16x32_bf16 v[38:41], v[158:161], v[206:209], v[38:41]
	v_mfma_f32_16x16x32_bf16 v[38:41], v[170:173], v[210:213], v[38:41]
	v_mfma_f32_16x16x32_bf16 v[46:49], v[154:157], v[210:213], v[46:49]
	v_mfma_f32_16x16x32_bf16 v[46:49], v[142:145], v[206:209], v[46:49]
	v_mfma_f32_16x16x32_bf16 v[30:33], v[142:145], v[214:217], v[30:33]
	v_mfma_f32_16x16x32_bf16 v[30:33], v[154:157], v[218:221], v[30:33]
	v_mfma_f32_16x16x32_bf16 v[22:25], v[170:173], v[218:221], v[22:25]
	v_mfma_f32_16x16x32_bf16 v[22:25], v[158:161], v[214:217], v[22:25]
	v_mfma_f32_16x16x32_bf16 v[6:9], v[158:161], v[222:225], v[6:9]
	v_mfma_f32_16x16x32_bf16 v[6:9], v[170:173], v[226:229], v[6:9]
	v_mfma_f32_16x16x32_bf16 v[14:17], v[154:157], v[226:229], v[14:17]
	v_mfma_f32_16x16x32_bf16 v[14:17], v[142:145], v[222:225], v[14:17]
	v_mfma_f32_16x16x32_bf16 v[10:13], v[178:181], v[222:225], v[10:13]
	v_mfma_f32_16x16x32_bf16 v[10:13], v[182:185], v[226:229], v[10:13]
	v_mfma_f32_16x16x32_bf16 v[2:5], v[230:233], v[226:229], v[2:5]
	v_mfma_f32_16x16x32_bf16 v[2:5], v[186:189], v[222:225], v[2:5]
	v_mfma_f32_16x16x32_bf16 v[18:21], v[186:189], v[214:217], v[18:21]
	v_mfma_f32_16x16x32_bf16 v[18:21], v[230:233], v[218:221], v[18:21]
	v_mfma_f32_16x16x32_bf16 v[26:29], v[182:185], v[218:221], v[26:29]
	v_mfma_f32_16x16x32_bf16 v[26:29], v[178:181], v[214:217], v[26:29]
	v_mfma_f32_16x16x32_bf16 v[42:45], v[178:181], v[206:209], v[42:45]
	v_mfma_f32_16x16x32_bf16 v[42:45], v[182:185], v[210:213], v[42:45]
	v_mfma_f32_16x16x32_bf16 v[34:37], v[230:233], v[210:213], v[34:37]
	v_mfma_f32_16x16x32_bf16 v[34:37], v[186:189], v[206:209], v[34:37]
	v_mfma_f32_16x16x32_bf16 v[50:53], v[186:189], v[192:195], v[50:53]
	v_mfma_f32_16x16x32_bf16 v[50:53], v[230:233], v[202:205], v[50:53]
	v_mfma_f32_16x16x32_bf16 v[58:61], v[182:185], v[202:205], v[58:61]
	v_mfma_f32_16x16x32_bf16 v[58:61], v[178:181], v[192:195], v[58:61]
	s_barrier
	s_add_i32 s61, s61, 2
	s_add_u32 s20, s20, 0x100
	s_addc_u32 s21, s21, 0
	s_add_u32 s57, s57, 0x100
	s_addc_u32 s60, s60, 0
.LBB0_1172:
	s_add_u32 s62, s20, 0xfff00000
	s_addc_u32 s63, s21, -1
	s_mov_b32 m0, s37
	ds_read_b128 v[142:145], v148
	global_load_lds_dwordx4 v130, s[62:63]
	s_mov_b32 m0, s38
	ds_read_b128 v[154:157], v148 offset:1024
	global_load_lds_dwordx4 v134, s[62:63]
	s_mov_b32 m0, s42
	ds_read_b128 v[158:161], v148 offset:2048
	global_load_lds_dwordx4 v138, s[20:21]
	s_mov_b32 m0, s43
	ds_read_b128 v[170:173], v148 offset:3072
	global_load_lds_dwordx4 v140, s[20:21]
	ds_read_b128 v[178:181], v149
	ds_read_b128 v[182:185], v149 offset:1024
	ds_read_b128 v[186:189], v149 offset:2048
	ds_read_b128 v[230:233], v149 offset:3072
	s_add_u32 s22, s20, 0xfff00080
	s_addc_u32 s23, s21, -1
	s_cmp_eq_u32 s61, 60
	s_cselect_b32 s25, s54, s23
	s_cselect_b32 s24, s55, s22
	s_cselect_b32 s23, s7, s60
	s_cselect_b32 s22, s56, s57
	ds_read_b128 v[192:195], v150
	ds_read_b128 v[202:205], v150 offset:1024
	ds_read_b128 v[206:209], v150 offset:2048
	ds_read_b128 v[210:213], v150 offset:3072
	ds_read_b128 v[214:217], v150 offset:4096
	ds_read_b128 v[218:221], v150 offset:5120
	ds_read_b128 v[222:225], v150 offset:6144
	ds_read_b128 v[226:229], v150 offset:7168
	s_waitcnt vmcnt(8)
	s_waitcnt lgkmcnt(0)
	s_barrier
	v_mfma_f32_16x16x32_bf16 v[126:129], v[142:145], v[192:195], v[126:129]
	v_mfma_f32_16x16x32_bf16 v[126:129], v[154:157], v[202:205], v[126:129]
	v_mfma_f32_16x16x32_bf16 v[118:121], v[170:173], v[202:205], v[118:121]
	v_mfma_f32_16x16x32_bf16 v[118:121], v[158:161], v[192:195], v[118:121]
	v_mfma_f32_16x16x32_bf16 v[102:105], v[158:161], v[206:209], v[102:105]
	v_mfma_f32_16x16x32_bf16 v[102:105], v[170:173], v[210:213], v[102:105]
	v_mfma_f32_16x16x32_bf16 v[110:113], v[154:157], v[210:213], v[110:113]
	v_mfma_f32_16x16x32_bf16 v[110:113], v[142:145], v[206:209], v[110:113]
	v_mfma_f32_16x16x32_bf16 v[94:97], v[142:145], v[214:217], v[94:97]
	v_mfma_f32_16x16x32_bf16 v[94:97], v[154:157], v[218:221], v[94:97]
	v_mfma_f32_16x16x32_bf16 v[86:89], v[170:173], v[218:221], v[86:89]
	v_mfma_f32_16x16x32_bf16 v[86:89], v[158:161], v[214:217], v[86:89]
	v_mfma_f32_16x16x32_bf16 v[70:73], v[158:161], v[222:225], v[70:73]
	v_mfma_f32_16x16x32_bf16 v[70:73], v[170:173], v[226:229], v[70:73]
	v_mfma_f32_16x16x32_bf16 v[78:81], v[154:157], v[226:229], v[78:81]
	v_mfma_f32_16x16x32_bf16 v[78:81], v[142:145], v[222:225], v[78:81]
	v_mfma_f32_16x16x32_bf16 v[74:77], v[178:181], v[222:225], v[74:77]
	v_mfma_f32_16x16x32_bf16 v[74:77], v[182:185], v[226:229], v[74:77]
	v_mfma_f32_16x16x32_bf16 v[66:69], v[230:233], v[226:229], v[66:69]
	v_mfma_f32_16x16x32_bf16 v[66:69], v[186:189], v[222:225], v[66:69]
	v_mfma_f32_16x16x32_bf16 v[82:85], v[186:189], v[214:217], v[82:85]
	v_mfma_f32_16x16x32_bf16 v[82:85], v[230:233], v[218:221], v[82:85]
	v_mfma_f32_16x16x32_bf16 v[90:93], v[182:185], v[218:221], v[90:93]
	v_mfma_f32_16x16x32_bf16 v[90:93], v[178:181], v[214:217], v[90:93]
	v_mfma_f32_16x16x32_bf16 v[106:109], v[178:181], v[206:209], v[106:109]
	v_mfma_f32_16x16x32_bf16 v[106:109], v[182:185], v[210:213], v[106:109]
	v_mfma_f32_16x16x32_bf16 v[98:101], v[230:233], v[210:213], v[98:101]
	v_mfma_f32_16x16x32_bf16 v[98:101], v[186:189], v[206:209], v[98:101]
	v_mfma_f32_16x16x32_bf16 v[114:117], v[186:189], v[192:195], v[114:117]
	v_mfma_f32_16x16x32_bf16 v[114:117], v[230:233], v[202:205], v[114:117]
	v_mfma_f32_16x16x32_bf16 v[122:125], v[182:185], v[202:205], v[122:125]
	v_mfma_f32_16x16x32_bf16 v[122:125], v[178:181], v[192:195], v[122:125]
	s_barrier
	s_mov_b32 m0, s44
	s_add_u32 s62, s22, 0x100000
	global_load_lds_dwordx4 v132, s[22:23]
	s_mov_b32 m0, s45
	s_addc_u32 s63, s23, 0
	global_load_lds_dwordx4 v136, s[22:23]
	s_mov_b32 m0, s46
	ds_read_b128 v[192:195], v150 offset:16384
	global_load_lds_dwordx4 v132, s[62:63]
	s_mov_b32 m0, s47
	ds_read_b128 v[202:205], v150 offset:17408
	global_load_lds_dwordx4 v136, s[62:63]
	ds_read_b128 v[206:209], v150 offset:18432
	ds_read_b128 v[210:213], v150 offset:19456
	ds_read_b128 v[214:217], v150 offset:20480
	ds_read_b128 v[218:221], v150 offset:21504
	ds_read_b128 v[222:225], v150 offset:22528
	ds_read_b128 v[226:229], v150 offset:23552
	s_waitcnt vmcnt(6)
	s_waitcnt lgkmcnt(0)
	s_barrier
	v_mfma_f32_16x16x32_bf16 v[62:65], v[142:145], v[192:195], v[62:65]
	v_mfma_f32_16x16x32_bf16 v[62:65], v[154:157], v[202:205], v[62:65]
	v_mfma_f32_16x16x32_bf16 v[54:57], v[170:173], v[202:205], v[54:57]
	v_mfma_f32_16x16x32_bf16 v[54:57], v[158:161], v[192:195], v[54:57]
	v_mfma_f32_16x16x32_bf16 v[38:41], v[158:161], v[206:209], v[38:41]
	v_mfma_f32_16x16x32_bf16 v[38:41], v[170:173], v[210:213], v[38:41]
	v_mfma_f32_16x16x32_bf16 v[46:49], v[154:157], v[210:213], v[46:49]
	v_mfma_f32_16x16x32_bf16 v[46:49], v[142:145], v[206:209], v[46:49]
	v_mfma_f32_16x16x32_bf16 v[30:33], v[142:145], v[214:217], v[30:33]
	v_mfma_f32_16x16x32_bf16 v[30:33], v[154:157], v[218:221], v[30:33]
	v_mfma_f32_16x16x32_bf16 v[22:25], v[170:173], v[218:221], v[22:25]
	v_mfma_f32_16x16x32_bf16 v[22:25], v[158:161], v[214:217], v[22:25]
	v_mfma_f32_16x16x32_bf16 v[6:9], v[158:161], v[222:225], v[6:9]
	v_mfma_f32_16x16x32_bf16 v[6:9], v[170:173], v[226:229], v[6:9]
	v_mfma_f32_16x16x32_bf16 v[14:17], v[154:157], v[226:229], v[14:17]
	v_mfma_f32_16x16x32_bf16 v[14:17], v[142:145], v[222:225], v[14:17]
	v_mfma_f32_16x16x32_bf16 v[10:13], v[178:181], v[222:225], v[10:13]
	v_mfma_f32_16x16x32_bf16 v[10:13], v[182:185], v[226:229], v[10:13]
	v_mfma_f32_16x16x32_bf16 v[2:5], v[230:233], v[226:229], v[2:5]
	v_mfma_f32_16x16x32_bf16 v[2:5], v[186:189], v[222:225], v[2:5]
	v_mfma_f32_16x16x32_bf16 v[18:21], v[186:189], v[214:217], v[18:21]
	v_mfma_f32_16x16x32_bf16 v[18:21], v[230:233], v[218:221], v[18:21]
	v_mfma_f32_16x16x32_bf16 v[26:29], v[182:185], v[218:221], v[26:29]
	v_mfma_f32_16x16x32_bf16 v[26:29], v[178:181], v[214:217], v[26:29]
	v_mfma_f32_16x16x32_bf16 v[42:45], v[178:181], v[206:209], v[42:45]
	v_mfma_f32_16x16x32_bf16 v[42:45], v[182:185], v[210:213], v[42:45]
	v_mfma_f32_16x16x32_bf16 v[34:37], v[230:233], v[210:213], v[34:37]
	v_mfma_f32_16x16x32_bf16 v[34:37], v[186:189], v[206:209], v[34:37]
	v_mfma_f32_16x16x32_bf16 v[50:53], v[186:189], v[192:195], v[50:53]
	v_mfma_f32_16x16x32_bf16 v[50:53], v[230:233], v[202:205], v[50:53]
	v_mfma_f32_16x16x32_bf16 v[58:61], v[182:185], v[202:205], v[58:61]
	v_mfma_f32_16x16x32_bf16 v[58:61], v[178:181], v[192:195], v[58:61]
	s_barrier
	s_mov_b32 m0, s31
	ds_read_b128 v[142:145], v151
	global_load_lds_dwordx4 v130, s[24:25]
	s_mov_b32 m0, s33
	ds_read_b128 v[154:157], v151 offset:1024
	global_load_lds_dwordx4 v134, s[24:25]
	s_add_u32 s24, s24, 0x100000
	s_addc_u32 s25, s25, 0
	s_mov_b32 m0, s34
	ds_read_b128 v[158:161], v151 offset:2048
	global_load_lds_dwordx4 v130, s[24:25]
	s_mov_b32 m0, s35
	ds_read_b128 v[170:173], v151 offset:3072
	global_load_lds_dwordx4 v134, s[24:25]
	ds_read_b128 v[178:181], v152
	ds_read_b128 v[182:185], v152 offset:1024
	ds_read_b128 v[186:189], v152 offset:2048
	ds_read_b128 v[230:233], v152 offset:3072
	ds_read_b128 v[192:195], v150 offset:32768
	ds_read_b128 v[202:205], v150 offset:33792
	ds_read_b128 v[206:209], v150 offset:34816
	ds_read_b128 v[210:213], v150 offset:35840
	ds_read_b128 v[214:217], v150 offset:36864
	ds_read_b128 v[218:221], v150 offset:37888
	ds_read_b128 v[222:225], v150 offset:38912
	ds_read_b128 v[226:229], v150 offset:39936
	s_waitcnt vmcnt(8)
	s_waitcnt lgkmcnt(0)
	s_barrier
	v_mfma_f32_16x16x32_bf16 v[126:129], v[142:145], v[192:195], v[126:129]
	v_mfma_f32_16x16x32_bf16 v[126:129], v[154:157], v[202:205], v[126:129]
	v_mfma_f32_16x16x32_bf16 v[118:121], v[170:173], v[202:205], v[118:121]
	v_mfma_f32_16x16x32_bf16 v[118:121], v[158:161], v[192:195], v[118:121]
	v_mfma_f32_16x16x32_bf16 v[102:105], v[158:161], v[206:209], v[102:105]
	v_mfma_f32_16x16x32_bf16 v[102:105], v[170:173], v[210:213], v[102:105]
	v_mfma_f32_16x16x32_bf16 v[110:113], v[154:157], v[210:213], v[110:113]
	v_mfma_f32_16x16x32_bf16 v[110:113], v[142:145], v[206:209], v[110:113]
	v_mfma_f32_16x16x32_bf16 v[94:97], v[142:145], v[214:217], v[94:97]
	v_mfma_f32_16x16x32_bf16 v[94:97], v[154:157], v[218:221], v[94:97]
	v_mfma_f32_16x16x32_bf16 v[86:89], v[170:173], v[218:221], v[86:89]
	v_mfma_f32_16x16x32_bf16 v[86:89], v[158:161], v[214:217], v[86:89]
	v_mfma_f32_16x16x32_bf16 v[70:73], v[158:161], v[222:225], v[70:73]
	v_mfma_f32_16x16x32_bf16 v[70:73], v[170:173], v[226:229], v[70:73]
	v_mfma_f32_16x16x32_bf16 v[78:81], v[154:157], v[226:229], v[78:81]
	v_mfma_f32_16x16x32_bf16 v[78:81], v[142:145], v[222:225], v[78:81]
	v_mfma_f32_16x16x32_bf16 v[74:77], v[178:181], v[222:225], v[74:77]
	v_mfma_f32_16x16x32_bf16 v[74:77], v[182:185], v[226:229], v[74:77]
	v_mfma_f32_16x16x32_bf16 v[66:69], v[230:233], v[226:229], v[66:69]
	v_mfma_f32_16x16x32_bf16 v[66:69], v[186:189], v[222:225], v[66:69]
	v_mfma_f32_16x16x32_bf16 v[82:85], v[186:189], v[214:217], v[82:85]
	v_mfma_f32_16x16x32_bf16 v[82:85], v[230:233], v[218:221], v[82:85]
	v_mfma_f32_16x16x32_bf16 v[90:93], v[182:185], v[218:221], v[90:93]
	v_mfma_f32_16x16x32_bf16 v[90:93], v[178:181], v[214:217], v[90:93]
	v_mfma_f32_16x16x32_bf16 v[106:109], v[178:181], v[206:209], v[106:109]
	v_mfma_f32_16x16x32_bf16 v[106:109], v[182:185], v[210:213], v[106:109]
	v_mfma_f32_16x16x32_bf16 v[98:101], v[230:233], v[210:213], v[98:101]
	v_mfma_f32_16x16x32_bf16 v[98:101], v[186:189], v[206:209], v[98:101]
	v_mfma_f32_16x16x32_bf16 v[114:117], v[186:189], v[192:195], v[114:117]
	v_mfma_f32_16x16x32_bf16 v[114:117], v[230:233], v[202:205], v[114:117]
	v_mfma_f32_16x16x32_bf16 v[122:125], v[182:185], v[202:205], v[122:125]
	v_mfma_f32_16x16x32_bf16 v[122:125], v[178:181], v[192:195], v[122:125]
	s_barrier
	s_mov_b32 m0, s48
	s_add_u32 s22, s22, 0x80
	s_addc_u32 s23, s23, 0
	global_load_lds_dwordx4 v132, s[22:23]
	s_mov_b32 m0, s49
	ds_read_b128 v[192:195], v150 offset:49152
	global_load_lds_dwordx4 v136, s[22:23]
	s_mov_b32 m0, s50
	s_add_u32 s22, s22, 0x100000
	s_addc_u32 s23, s23, 0
	global_load_lds_dwordx4 v132, s[22:23]
	s_mov_b32 m0, s51
	ds_read_b128 v[202:205], v150 offset:50176
	global_load_lds_dwordx4 v136, s[22:23]
	ds_read_b128 v[206:209], v150 offset:51200
	ds_read_b128 v[210:213], v150 offset:52224
	ds_read_b128 v[214:217], v150 offset:53248
	ds_read_b128 v[218:221], v150 offset:54272
	ds_read_b128 v[222:225], v150 offset:55296
	ds_read_b128 v[226:229], v150 offset:56320
	s_waitcnt vmcnt(6)
	s_waitcnt lgkmcnt(0)
	s_barrier
	v_mfma_f32_16x16x32_bf16 v[62:65], v[142:145], v[192:195], v[62:65]
	v_mfma_f32_16x16x32_bf16 v[62:65], v[154:157], v[202:205], v[62:65]
	v_mfma_f32_16x16x32_bf16 v[54:57], v[170:173], v[202:205], v[54:57]
	v_mfma_f32_16x16x32_bf16 v[54:57], v[158:161], v[192:195], v[54:57]
	v_mfma_f32_16x16x32_bf16 v[38:41], v[158:161], v[206:209], v[38:41]
	v_mfma_f32_16x16x32_bf16 v[38:41], v[170:173], v[210:213], v[38:41]
	v_mfma_f32_16x16x32_bf16 v[46:49], v[154:157], v[210:213], v[46:49]
	v_mfma_f32_16x16x32_bf16 v[46:49], v[142:145], v[206:209], v[46:49]
	v_mfma_f32_16x16x32_bf16 v[30:33], v[142:145], v[214:217], v[30:33]
	v_mfma_f32_16x16x32_bf16 v[30:33], v[154:157], v[218:221], v[30:33]
	v_mfma_f32_16x16x32_bf16 v[22:25], v[170:173], v[218:221], v[22:25]
	v_mfma_f32_16x16x32_bf16 v[22:25], v[158:161], v[214:217], v[22:25]
	v_mfma_f32_16x16x32_bf16 v[6:9], v[158:161], v[222:225], v[6:9]
	v_mfma_f32_16x16x32_bf16 v[6:9], v[170:173], v[226:229], v[6:9]
	v_mfma_f32_16x16x32_bf16 v[14:17], v[154:157], v[226:229], v[14:17]
	v_mfma_f32_16x16x32_bf16 v[14:17], v[142:145], v[222:225], v[14:17]
	v_mfma_f32_16x16x32_bf16 v[10:13], v[178:181], v[222:225], v[10:13]
	v_mfma_f32_16x16x32_bf16 v[10:13], v[182:185], v[226:229], v[10:13]
	v_mfma_f32_16x16x32_bf16 v[2:5], v[230:233], v[226:229], v[2:5]
	v_mfma_f32_16x16x32_bf16 v[2:5], v[186:189], v[222:225], v[2:5]
	v_mfma_f32_16x16x32_bf16 v[18:21], v[186:189], v[214:217], v[18:21]
	v_mfma_f32_16x16x32_bf16 v[18:21], v[230:233], v[218:221], v[18:21]
	v_mfma_f32_16x16x32_bf16 v[26:29], v[182:185], v[218:221], v[26:29]
	v_mfma_f32_16x16x32_bf16 v[26:29], v[178:181], v[214:217], v[26:29]
	v_mfma_f32_16x16x32_bf16 v[42:45], v[178:181], v[206:209], v[42:45]
	v_mfma_f32_16x16x32_bf16 v[42:45], v[182:185], v[210:213], v[42:45]
	v_mfma_f32_16x16x32_bf16 v[34:37], v[230:233], v[210:213], v[34:37]
	v_mfma_f32_16x16x32_bf16 v[34:37], v[186:189], v[206:209], v[34:37]
	v_mfma_f32_16x16x32_bf16 v[50:53], v[186:189], v[192:195], v[50:53]
	v_mfma_f32_16x16x32_bf16 v[50:53], v[230:233], v[202:205], v[50:53]
	v_mfma_f32_16x16x32_bf16 v[58:61], v[182:185], v[202:205], v[58:61]
	v_mfma_f32_16x16x32_bf16 v[58:61], v[178:181], v[192:195], v[58:61]
	s_barrier
	s_add_i32 s61, s61, 2
	s_add_u32 s20, s20, 0x100
	s_addc_u32 s21, s21, 0
	s_add_u32 s57, s57, 0x100
	s_addc_u32 s60, s60, 0
	s_cmp_gt_u32 s61, 61
	s_cbranch_scc0 .LBB0_1172
	s_and_b64 vcc, exec, s[16:17]
	s_cbranch_vccz .LBB0_1175
	s_barrier

.LBB0_2372:
	s_add_i32 s34, s34, 1
	s_mov_b32 s50, s6
	s_lshl_b32 s6, s34, 5
	s_add_i32 s6, s6, s3
	s_mov_b64 s[22:23], s[8:9]
	s_lshl_b32 s8, s6, 3
	s_ashr_i32 s7, s6, 2
	s_add_i32 s8, s8, s37
	s_cmpk_lt_i32 s6, 0x158
	s_cselect_b32 s6, s7, s8
	s_mov_b32 s51, s26
	s_cselect_b32 s26, s38, 32
	s_cmpk_lt_i32 s6, 0x56
	s_cselect_b64 s[18:19], -1, 0
	s_lshl_b32 s7, s26, 21
	v_readlane_b32 s0, v250, 46
	s_mov_b64 s[20:21], s[10:11]
	v_readlane_b32 s1, v250, 47
	s_add_u32 s10, s0, s7
	s_addc_u32 s11, s1, 0
	s_and_b64 s[8:9], s[18:19], exec
	s_cselect_b32 s52, s11, s21
	s_cselect_b32 s53, s10, s20
	s_ashr_i32 s7, s6, 31
	s_lshl_b64 s[8:9], s[6:7], 21
	s_add_u32 s8, s27, s8
	s_addc_u32 s9, s28, s9
	s_and_b64 s[24:25], s[18:19], exec
	s_cselect_b32 s7, s9, s23
	s_cselect_b32 s54, s8, s22
	s_add_u32 s20, s20, 0x100080
	s_addc_u32 s21, s21, 0
	s_add_u32 s55, s22, 0x100
	s_addc_u32 s56, s23, 0
	s_mov_b32 s57, -2
	s_waitcnt lgkmcnt(0)
	s_add_u32 s60, s20, 0xfff00000
	s_addc_u32 s61, s21, -1
	s_mov_b32 m0, s35
	ds_read_b128 v[142:145], v148
	global_load_lds_dwordx4 v130, s[60:61]
	s_mov_b32 m0, s36
	ds_read_b128 v[154:157], v148 offset:1024
	global_load_lds_dwordx4 v134, s[60:61]
	s_mov_b32 m0, s40
	ds_read_b128 v[158:161], v148 offset:2048
	global_load_lds_dwordx4 v138, s[20:21]
	s_mov_b32 m0, s41
	ds_read_b128 v[170:173], v148 offset:3072
	global_load_lds_dwordx4 v140, s[20:21]
	ds_read_b128 v[178:181], v149
	ds_read_b128 v[182:185], v149 offset:1024
	ds_read_b128 v[186:189], v149 offset:2048
	ds_read_b128 v[234:237], v149 offset:3072
	s_add_u32 s22, s20, 0xfff00080
	s_addc_u32 s23, s21, -1
	s_cmp_eq_u32 s57, 60
	s_cselect_b32 s25, s52, s23
	s_cselect_b32 s24, s53, s22
	s_cselect_b32 s23, s7, s56
	s_cselect_b32 s22, s54, s55
	ds_read_b128 v[192:195], v150
	ds_read_b128 v[204:207], v150 offset:1024
	ds_read_b128 v[208:211], v150 offset:2048
	ds_read_b128 v[212:215], v150 offset:3072
	ds_read_b128 v[216:219], v150 offset:4096
	ds_read_b128 v[220:223], v150 offset:5120
	ds_read_b128 v[224:227], v150 offset:6144
	ds_read_b128 v[228:231], v150 offset:7168
	s_waitcnt vmcnt(8)
	s_waitcnt lgkmcnt(0)
	s_barrier
	v_mfma_f32_16x16x32_bf16 v[126:129], v[142:145], v[192:195], 0
	v_mfma_f32_16x16x32_bf16 v[126:129], v[154:157], v[204:207], v[126:129]
	v_mfma_f32_16x16x32_bf16 v[122:125], v[170:173], v[204:207], 0
	v_mfma_f32_16x16x32_bf16 v[122:125], v[158:161], v[192:195], v[122:125]
	v_mfma_f32_16x16x32_bf16 v[106:109], v[158:161], v[208:211], 0
	v_mfma_f32_16x16x32_bf16 v[106:109], v[170:173], v[212:215], v[106:109]
	v_mfma_f32_16x16x32_bf16 v[110:113], v[154:157], v[212:215], 0
	v_mfma_f32_16x16x32_bf16 v[110:113], v[142:145], v[208:211], v[110:113]
	v_mfma_f32_16x16x32_bf16 v[94:97], v[142:145], v[216:219], 0
	v_mfma_f32_16x16x32_bf16 v[94:97], v[154:157], v[220:223], v[94:97]
	v_mfma_f32_16x16x32_bf16 v[90:93], v[170:173], v[220:223], 0
	v_mfma_f32_16x16x32_bf16 v[90:93], v[158:161], v[216:219], v[90:93]
	v_mfma_f32_16x16x32_bf16 v[74:77], v[158:161], v[224:227], 0
	v_mfma_f32_16x16x32_bf16 v[74:77], v[170:173], v[228:231], v[74:77]
	v_mfma_f32_16x16x32_bf16 v[78:81], v[154:157], v[228:231], 0
	v_mfma_f32_16x16x32_bf16 v[78:81], v[142:145], v[224:227], v[78:81]
	v_mfma_f32_16x16x32_bf16 v[70:73], v[178:181], v[224:227], 0
	v_mfma_f32_16x16x32_bf16 v[70:73], v[182:185], v[228:231], v[70:73]
	v_mfma_f32_16x16x32_bf16 v[66:69], v[234:237], v[228:231], 0
	v_mfma_f32_16x16x32_bf16 v[66:69], v[186:189], v[224:227], v[66:69]
	v_mfma_f32_16x16x32_bf16 v[82:85], v[186:189], v[216:219], 0
	v_mfma_f32_16x16x32_bf16 v[82:85], v[234:237], v[220:223], v[82:85]
	v_mfma_f32_16x16x32_bf16 v[86:89], v[182:185], v[220:223], 0
	v_mfma_f32_16x16x32_bf16 v[86:89], v[178:181], v[216:219], v[86:89]
	v_mfma_f32_16x16x32_bf16 v[102:105], v[178:181], v[208:211], 0
	v_mfma_f32_16x16x32_bf16 v[102:105], v[182:185], v[212:215], v[102:105]
	v_mfma_f32_16x16x32_bf16 v[98:101], v[234:237], v[212:215], 0
	v_mfma_f32_16x16x32_bf16 v[98:101], v[186:189], v[208:211], v[98:101]
	v_mfma_f32_16x16x32_bf16 v[114:117], v[186:189], v[192:195], 0
	v_mfma_f32_16x16x32_bf16 v[114:117], v[234:237], v[204:207], v[114:117]
	v_mfma_f32_16x16x32_bf16 v[118:121], v[182:185], v[204:207], 0
	v_mfma_f32_16x16x32_bf16 v[118:121], v[178:181], v[192:195], v[118:121]
	s_barrier
	s_mov_b32 m0, s42
	s_add_u32 s60, s22, 0x100000
	global_load_lds_dwordx4 v132, s[22:23]
	s_mov_b32 m0, s43
	s_addc_u32 s61, s23, 0
	global_load_lds_dwordx4 v136, s[22:23]
	s_mov_b32 m0, s44
	ds_read_b128 v[192:195], v150 offset:16384
	global_load_lds_dwordx4 v132, s[60:61]
	s_mov_b32 m0, s45
	ds_read_b128 v[204:207], v150 offset:17408
	global_load_lds_dwordx4 v136, s[60:61]
	ds_read_b128 v[208:211], v150 offset:18432
	ds_read_b128 v[212:215], v150 offset:19456
	ds_read_b128 v[216:219], v150 offset:20480
	ds_read_b128 v[220:223], v150 offset:21504
	ds_read_b128 v[224:227], v150 offset:22528
	ds_read_b128 v[228:231], v150 offset:23552
	s_waitcnt vmcnt(6)
	s_waitcnt lgkmcnt(0)
	s_barrier
	v_mfma_f32_16x16x32_bf16 v[62:65], v[142:145], v[192:195], 0
	v_mfma_f32_16x16x32_bf16 v[62:65], v[154:157], v[204:207], v[62:65]
	v_mfma_f32_16x16x32_bf16 v[58:61], v[170:173], v[204:207], 0
	v_mfma_f32_16x16x32_bf16 v[58:61], v[158:161], v[192:195], v[58:61]
	v_mfma_f32_16x16x32_bf16 v[42:45], v[158:161], v[208:211], 0
	v_mfma_f32_16x16x32_bf16 v[42:45], v[170:173], v[212:215], v[42:45]
	v_mfma_f32_16x16x32_bf16 v[46:49], v[154:157], v[212:215], 0
	v_mfma_f32_16x16x32_bf16 v[46:49], v[142:145], v[208:211], v[46:49]
	v_mfma_f32_16x16x32_bf16 v[30:33], v[142:145], v[216:219], 0
	v_mfma_f32_16x16x32_bf16 v[30:33], v[154:157], v[220:223], v[30:33]
	v_mfma_f32_16x16x32_bf16 v[26:29], v[170:173], v[220:223], 0
	v_mfma_f32_16x16x32_bf16 v[26:29], v[158:161], v[216:219], v[26:29]
	v_mfma_f32_16x16x32_bf16 v[10:13], v[158:161], v[224:227], 0
	v_mfma_f32_16x16x32_bf16 v[10:13], v[170:173], v[228:231], v[10:13]
	v_mfma_f32_16x16x32_bf16 v[14:17], v[154:157], v[228:231], 0
	v_mfma_f32_16x16x32_bf16 v[14:17], v[142:145], v[224:227], v[14:17]
	v_mfma_f32_16x16x32_bf16 v[6:9], v[178:181], v[224:227], 0
	v_mfma_f32_16x16x32_bf16 v[6:9], v[182:185], v[228:231], v[6:9]
	v_mfma_f32_16x16x32_bf16 v[2:5], v[234:237], v[228:231], 0
	v_mfma_f32_16x16x32_bf16 v[2:5], v[186:189], v[224:227], v[2:5]
	v_mfma_f32_16x16x32_bf16 v[18:21], v[186:189], v[216:219], 0
	v_mfma_f32_16x16x32_bf16 v[18:21], v[234:237], v[220:223], v[18:21]
	v_mfma_f32_16x16x32_bf16 v[22:25], v[182:185], v[220:223], 0
	v_mfma_f32_16x16x32_bf16 v[22:25], v[178:181], v[216:219], v[22:25]
	v_mfma_f32_16x16x32_bf16 v[38:41], v[178:181], v[208:211], 0
	v_mfma_f32_16x16x32_bf16 v[38:41], v[182:185], v[212:215], v[38:41]
	v_mfma_f32_16x16x32_bf16 v[34:37], v[234:237], v[212:215], 0
	v_mfma_f32_16x16x32_bf16 v[34:37], v[186:189], v[208:211], v[34:37]
	v_mfma_f32_16x16x32_bf16 v[50:53], v[186:189], v[192:195], 0
	v_mfma_f32_16x16x32_bf16 v[50:53], v[234:237], v[204:207], v[50:53]
	v_mfma_f32_16x16x32_bf16 v[54:57], v[182:185], v[204:207], 0
	v_mfma_f32_16x16x32_bf16 v[54:57], v[178:181], v[192:195], v[54:57]
	s_barrier
	s_mov_b32 m0, s29
	ds_read_b128 v[142:145], v151
	global_load_lds_dwordx4 v130, s[24:25]
	s_mov_b32 m0, s30
	ds_read_b128 v[154:157], v151 offset:1024
	global_load_lds_dwordx4 v134, s[24:25]
	s_add_u32 s24, s24, 0x100000
	s_addc_u32 s25, s25, 0
	s_mov_b32 m0, s31
	ds_read_b128 v[158:161], v151 offset:2048
	global_load_lds_dwordx4 v130, s[24:25]
	s_mov_b32 m0, s33
	ds_read_b128 v[170:173], v151 offset:3072
	global_load_lds_dwordx4 v134, s[24:25]
	ds_read_b128 v[178:181], v152
	ds_read_b128 v[182:185], v152 offset:1024
	ds_read_b128 v[186:189], v152 offset:2048
	ds_read_b128 v[234:237], v152 offset:3072
	ds_read_b128 v[192:195], v150 offset:32768
	ds_read_b128 v[204:207], v150 offset:33792
	ds_read_b128 v[208:211], v150 offset:34816
	ds_read_b128 v[212:215], v150 offset:35840
	ds_read_b128 v[216:219], v150 offset:36864
	ds_read_b128 v[220:223], v150 offset:37888
	ds_read_b128 v[224:227], v150 offset:38912
	ds_read_b128 v[228:231], v150 offset:39936
	s_waitcnt vmcnt(8)
	s_waitcnt lgkmcnt(0)
	s_barrier
	v_mfma_f32_16x16x32_bf16 v[126:129], v[142:145], v[192:195], v[126:129]
	v_mfma_f32_16x16x32_bf16 v[126:129], v[154:157], v[204:207], v[126:129]
	v_mfma_f32_16x16x32_bf16 v[122:125], v[170:173], v[204:207], v[122:125]
	v_mfma_f32_16x16x32_bf16 v[122:125], v[158:161], v[192:195], v[122:125]
	v_mfma_f32_16x16x32_bf16 v[106:109], v[158:161], v[208:211], v[106:109]
	v_mfma_f32_16x16x32_bf16 v[106:109], v[170:173], v[212:215], v[106:109]
	v_mfma_f32_16x16x32_bf16 v[110:113], v[154:157], v[212:215], v[110:113]
	v_mfma_f32_16x16x32_bf16 v[110:113], v[142:145], v[208:211], v[110:113]
	v_mfma_f32_16x16x32_bf16 v[94:97], v[142:145], v[216:219], v[94:97]
	v_mfma_f32_16x16x32_bf16 v[94:97], v[154:157], v[220:223], v[94:97]
	v_mfma_f32_16x16x32_bf16 v[90:93], v[170:173], v[220:223], v[90:93]
	v_mfma_f32_16x16x32_bf16 v[90:93], v[158:161], v[216:219], v[90:93]
	v_mfma_f32_16x16x32_bf16 v[74:77], v[158:161], v[224:227], v[74:77]
	v_mfma_f32_16x16x32_bf16 v[74:77], v[170:173], v[228:231], v[74:77]
	v_mfma_f32_16x16x32_bf16 v[78:81], v[154:157], v[228:231], v[78:81]
	v_mfma_f32_16x16x32_bf16 v[78:81], v[142:145], v[224:227], v[78:81]
	v_mfma_f32_16x16x32_bf16 v[70:73], v[178:181], v[224:227], v[70:73]
	v_mfma_f32_16x16x32_bf16 v[70:73], v[182:185], v[228:231], v[70:73]
	v_mfma_f32_16x16x32_bf16 v[66:69], v[234:237], v[228:231], v[66:69]
	v_mfma_f32_16x16x32_bf16 v[66:69], v[186:189], v[224:227], v[66:69]
	v_mfma_f32_16x16x32_bf16 v[82:85], v[186:189], v[216:219], v[82:85]
	v_mfma_f32_16x16x32_bf16 v[82:85], v[234:237], v[220:223], v[82:85]
	v_mfma_f32_16x16x32_bf16 v[86:89], v[182:185], v[220:223], v[86:89]
	v_mfma_f32_16x16x32_bf16 v[86:89], v[178:181], v[216:219], v[86:89]
	v_mfma_f32_16x16x32_bf16 v[102:105], v[178:181], v[208:211], v[102:105]
	v_mfma_f32_16x16x32_bf16 v[102:105], v[182:185], v[212:215], v[102:105]
	v_mfma_f32_16x16x32_bf16 v[98:101], v[234:237], v[212:215], v[98:101]
	v_mfma_f32_16x16x32_bf16 v[98:101], v[186:189], v[208:211], v[98:101]
	v_mfma_f32_16x16x32_bf16 v[114:117], v[186:189], v[192:195], v[114:117]
	v_mfma_f32_16x16x32_bf16 v[114:117], v[234:237], v[204:207], v[114:117]
	v_mfma_f32_16x16x32_bf16 v[118:121], v[182:185], v[204:207], v[118:121]
	v_mfma_f32_16x16x32_bf16 v[118:121], v[178:181], v[192:195], v[118:121]
	s_barrier
	s_mov_b32 m0, s46
	s_add_u32 s22, s22, 0x80
	s_addc_u32 s23, s23, 0
	global_load_lds_dwordx4 v132, s[22:23]
	s_mov_b32 m0, s47
	ds_read_b128 v[192:195], v150 offset:49152
	global_load_lds_dwordx4 v136, s[22:23]
	s_mov_b32 m0, s48
	s_add_u32 s22, s22, 0x100000
	s_addc_u32 s23, s23, 0
	global_load_lds_dwordx4 v132, s[22:23]
	s_mov_b32 m0, s49
	ds_read_b128 v[204:207], v150 offset:50176
	global_load_lds_dwordx4 v136, s[22:23]
	ds_read_b128 v[208:211], v150 offset:51200
	ds_read_b128 v[212:215], v150 offset:52224
	ds_read_b128 v[216:219], v150 offset:53248
	ds_read_b128 v[220:223], v150 offset:54272
	ds_read_b128 v[224:227], v150 offset:55296
	ds_read_b128 v[228:231], v150 offset:56320
	s_waitcnt vmcnt(6)
	s_waitcnt lgkmcnt(0)
	s_barrier
	v_mfma_f32_16x16x32_bf16 v[62:65], v[142:145], v[192:195], v[62:65]
	v_mfma_f32_16x16x32_bf16 v[62:65], v[154:157], v[204:207], v[62:65]
	v_mfma_f32_16x16x32_bf16 v[58:61], v[170:173], v[204:207], v[58:61]
	v_mfma_f32_16x16x32_bf16 v[58:61], v[158:161], v[192:195], v[58:61]
	v_mfma_f32_16x16x32_bf16 v[42:45], v[158:161], v[208:211], v[42:45]
	v_mfma_f32_16x16x32_bf16 v[42:45], v[170:173], v[212:215], v[42:45]
	v_mfma_f32_16x16x32_bf16 v[46:49], v[154:157], v[212:215], v[46:49]
	v_mfma_f32_16x16x32_bf16 v[46:49], v[142:145], v[208:211], v[46:49]
	v_mfma_f32_16x16x32_bf16 v[30:33], v[142:145], v[216:219], v[30:33]
	v_mfma_f32_16x16x32_bf16 v[30:33], v[154:157], v[220:223], v[30:33]
	v_mfma_f32_16x16x32_bf16 v[26:29], v[170:173], v[220:223], v[26:29]
	v_mfma_f32_16x16x32_bf16 v[26:29], v[158:161], v[216:219], v[26:29]
	v_mfma_f32_16x16x32_bf16 v[10:13], v[158:161], v[224:227], v[10:13]
	v_mfma_f32_16x16x32_bf16 v[10:13], v[170:173], v[228:231], v[10:13]
	v_mfma_f32_16x16x32_bf16 v[14:17], v[154:157], v[228:231], v[14:17]
	v_mfma_f32_16x16x32_bf16 v[14:17], v[142:145], v[224:227], v[14:17]
	v_mfma_f32_16x16x32_bf16 v[6:9], v[178:181], v[224:227], v[6:9]
	v_mfma_f32_16x16x32_bf16 v[6:9], v[182:185], v[228:231], v[6:9]
	v_mfma_f32_16x16x32_bf16 v[2:5], v[234:237], v[228:231], v[2:5]
	v_mfma_f32_16x16x32_bf16 v[2:5], v[186:189], v[224:227], v[2:5]
	v_mfma_f32_16x16x32_bf16 v[18:21], v[186:189], v[216:219], v[18:21]
	v_mfma_f32_16x16x32_bf16 v[18:21], v[234:237], v[220:223], v[18:21]
	v_mfma_f32_16x16x32_bf16 v[22:25], v[182:185], v[220:223], v[22:25]
	v_mfma_f32_16x16x32_bf16 v[22:25], v[178:181], v[216:219], v[22:25]
	v_mfma_f32_16x16x32_bf16 v[38:41], v[178:181], v[208:211], v[38:41]
	v_mfma_f32_16x16x32_bf16 v[38:41], v[182:185], v[212:215], v[38:41]
	v_mfma_f32_16x16x32_bf16 v[34:37], v[234:237], v[212:215], v[34:37]
	v_mfma_f32_16x16x32_bf16 v[34:37], v[186:189], v[208:211], v[34:37]
	v_mfma_f32_16x16x32_bf16 v[50:53], v[186:189], v[192:195], v[50:53]
	v_mfma_f32_16x16x32_bf16 v[50:53], v[234:237], v[204:207], v[50:53]
	v_mfma_f32_16x16x32_bf16 v[54:57], v[182:185], v[204:207], v[54:57]
	v_mfma_f32_16x16x32_bf16 v[54:57], v[178:181], v[192:195], v[54:57]
	s_barrier
	s_add_i32 s57, s57, 2
	s_add_u32 s20, s20, 0x100
	s_addc_u32 s21, s21, 0
	s_add_u32 s55, s55, 0x100
	s_addc_u32 s56, s56, 0
.LBB0_2373:
	s_add_u32 s60, s20, 0xfff00000
	s_addc_u32 s61, s21, -1
	s_mov_b32 m0, s35
	ds_read_b128 v[142:145], v148
	global_load_lds_dwordx4 v130, s[60:61]
	s_mov_b32 m0, s36
	ds_read_b128 v[154:157], v148 offset:1024
	global_load_lds_dwordx4 v134, s[60:61]
	s_mov_b32 m0, s40
	ds_read_b128 v[158:161], v148 offset:2048
	global_load_lds_dwordx4 v138, s[20:21]
	s_mov_b32 m0, s41
	ds_read_b128 v[170:173], v148 offset:3072
	global_load_lds_dwordx4 v140, s[20:21]
	ds_read_b128 v[178:181], v149
	ds_read_b128 v[182:185], v149 offset:1024
	ds_read_b128 v[186:189], v149 offset:2048
	ds_read_b128 v[234:237], v149 offset:3072
	s_add_u32 s22, s20, 0xfff00080
	s_addc_u32 s23, s21, -1
	s_cmp_eq_u32 s57, 60
	s_cselect_b32 s25, s52, s23
	s_cselect_b32 s24, s53, s22
	s_cselect_b32 s23, s7, s56
	s_cselect_b32 s22, s54, s55
	ds_read_b128 v[192:195], v150
	ds_read_b128 v[204:207], v150 offset:1024
	ds_read_b128 v[208:211], v150 offset:2048
	ds_read_b128 v[212:215], v150 offset:3072
	ds_read_b128 v[216:219], v150 offset:4096
	ds_read_b128 v[220:223], v150 offset:5120
	ds_read_b128 v[224:227], v150 offset:6144
	ds_read_b128 v[228:231], v150 offset:7168
	s_waitcnt vmcnt(8)
	s_waitcnt lgkmcnt(0)
	s_barrier
	v_mfma_f32_16x16x32_bf16 v[126:129], v[142:145], v[192:195], v[126:129]
	v_mfma_f32_16x16x32_bf16 v[126:129], v[154:157], v[204:207], v[126:129]
	v_mfma_f32_16x16x32_bf16 v[122:125], v[170:173], v[204:207], v[122:125]
	v_mfma_f32_16x16x32_bf16 v[122:125], v[158:161], v[192:195], v[122:125]
	v_mfma_f32_16x16x32_bf16 v[106:109], v[158:161], v[208:211], v[106:109]
	v_mfma_f32_16x16x32_bf16 v[106:109], v[170:173], v[212:215], v[106:109]
	v_mfma_f32_16x16x32_bf16 v[110:113], v[154:157], v[212:215], v[110:113]
	v_mfma_f32_16x16x32_bf16 v[110:113], v[142:145], v[208:211], v[110:113]
	v_mfma_f32_16x16x32_bf16 v[94:97], v[142:145], v[216:219], v[94:97]
	v_mfma_f32_16x16x32_bf16 v[94:97], v[154:157], v[220:223], v[94:97]
	v_mfma_f32_16x16x32_bf16 v[90:93], v[170:173], v[220:223], v[90:93]
	v_mfma_f32_16x16x32_bf16 v[90:93], v[158:161], v[216:219], v[90:93]
	v_mfma_f32_16x16x32_bf16 v[74:77], v[158:161], v[224:227], v[74:77]
	v_mfma_f32_16x16x32_bf16 v[74:77], v[170:173], v[228:231], v[74:77]
	v_mfma_f32_16x16x32_bf16 v[78:81], v[154:157], v[228:231], v[78:81]
	v_mfma_f32_16x16x32_bf16 v[78:81], v[142:145], v[224:227], v[78:81]
	v_mfma_f32_16x16x32_bf16 v[70:73], v[178:181], v[224:227], v[70:73]
	v_mfma_f32_16x16x32_bf16 v[70:73], v[182:185], v[228:231], v[70:73]
	v_mfma_f32_16x16x32_bf16 v[66:69], v[234:237], v[228:231], v[66:69]
	v_mfma_f32_16x16x32_bf16 v[66:69], v[186:189], v[224:227], v[66:69]
	v_mfma_f32_16x16x32_bf16 v[82:85], v[186:189], v[216:219], v[82:85]
	v_mfma_f32_16x16x32_bf16 v[82:85], v[234:237], v[220:223], v[82:85]
	v_mfma_f32_16x16x32_bf16 v[86:89], v[182:185], v[220:223], v[86:89]
	v_mfma_f32_16x16x32_bf16 v[86:89], v[178:181], v[216:219], v[86:89]
	v_mfma_f32_16x16x32_bf16 v[102:105], v[178:181], v[208:211], v[102:105]
	v_mfma_f32_16x16x32_bf16 v[102:105], v[182:185], v[212:215], v[102:105]
	v_mfma_f32_16x16x32_bf16 v[98:101], v[234:237], v[212:215], v[98:101]
	v_mfma_f32_16x16x32_bf16 v[98:101], v[186:189], v[208:211], v[98:101]
	v_mfma_f32_16x16x32_bf16 v[114:117], v[186:189], v[192:195], v[114:117]
	v_mfma_f32_16x16x32_bf16 v[114:117], v[234:237], v[204:207], v[114:117]
	v_mfma_f32_16x16x32_bf16 v[118:121], v[182:185], v[204:207], v[118:121]
	v_mfma_f32_16x16x32_bf16 v[118:121], v[178:181], v[192:195], v[118:121]
	s_barrier
	s_mov_b32 m0, s42
	s_add_u32 s60, s22, 0x100000
	global_load_lds_dwordx4 v132, s[22:23]
	s_mov_b32 m0, s43
	s_addc_u32 s61, s23, 0
	global_load_lds_dwordx4 v136, s[22:23]
	s_mov_b32 m0, s44
	ds_read_b128 v[192:195], v150 offset:16384
	global_load_lds_dwordx4 v132, s[60:61]
	s_mov_b32 m0, s45
	ds_read_b128 v[204:207], v150 offset:17408
	global_load_lds_dwordx4 v136, s[60:61]
	ds_read_b128 v[208:211], v150 offset:18432
	ds_read_b128 v[212:215], v150 offset:19456
	ds_read_b128 v[216:219], v150 offset:20480
	ds_read_b128 v[220:223], v150 offset:21504
	ds_read_b128 v[224:227], v150 offset:22528
	ds_read_b128 v[228:231], v150 offset:23552
	s_waitcnt vmcnt(6)
	s_waitcnt lgkmcnt(0)
	s_barrier
	v_mfma_f32_16x16x32_bf16 v[62:65], v[142:145], v[192:195], v[62:65]
	v_mfma_f32_16x16x32_bf16 v[62:65], v[154:157], v[204:207], v[62:65]
	v_mfma_f32_16x16x32_bf16 v[58:61], v[170:173], v[204:207], v[58:61]
	v_mfma_f32_16x16x32_bf16 v[58:61], v[158:161], v[192:195], v[58:61]
	v_mfma_f32_16x16x32_bf16 v[42:45], v[158:161], v[208:211], v[42:45]
	v_mfma_f32_16x16x32_bf16 v[42:45], v[170:173], v[212:215], v[42:45]
	v_mfma_f32_16x16x32_bf16 v[46:49], v[154:157], v[212:215], v[46:49]
	v_mfma_f32_16x16x32_bf16 v[46:49], v[142:145], v[208:211], v[46:49]
	v_mfma_f32_16x16x32_bf16 v[30:33], v[142:145], v[216:219], v[30:33]
	v_mfma_f32_16x16x32_bf16 v[30:33], v[154:157], v[220:223], v[30:33]
	v_mfma_f32_16x16x32_bf16 v[26:29], v[170:173], v[220:223], v[26:29]
	v_mfma_f32_16x16x32_bf16 v[26:29], v[158:161], v[216:219], v[26:29]
	v_mfma_f32_16x16x32_bf16 v[10:13], v[158:161], v[224:227], v[10:13]
	v_mfma_f32_16x16x32_bf16 v[10:13], v[170:173], v[228:231], v[10:13]
	v_mfma_f32_16x16x32_bf16 v[14:17], v[154:157], v[228:231], v[14:17]
	v_mfma_f32_16x16x32_bf16 v[14:17], v[142:145], v[224:227], v[14:17]
	v_mfma_f32_16x16x32_bf16 v[6:9], v[178:181], v[224:227], v[6:9]
	v_mfma_f32_16x16x32_bf16 v[6:9], v[182:185], v[228:231], v[6:9]
	v_mfma_f32_16x16x32_bf16 v[2:5], v[234:237], v[228:231], v[2:5]
	v_mfma_f32_16x16x32_bf16 v[2:5], v[186:189], v[224:227], v[2:5]
	v_mfma_f32_16x16x32_bf16 v[18:21], v[186:189], v[216:219], v[18:21]
	v_mfma_f32_16x16x32_bf16 v[18:21], v[234:237], v[220:223], v[18:21]
	v_mfma_f32_16x16x32_bf16 v[22:25], v[182:185], v[220:223], v[22:25]
	v_mfma_f32_16x16x32_bf16 v[22:25], v[178:181], v[216:219], v[22:25]
	v_mfma_f32_16x16x32_bf16 v[38:41], v[178:181], v[208:211], v[38:41]
	v_mfma_f32_16x16x32_bf16 v[38:41], v[182:185], v[212:215], v[38:41]
	v_mfma_f32_16x16x32_bf16 v[34:37], v[234:237], v[212:215], v[34:37]
	v_mfma_f32_16x16x32_bf16 v[34:37], v[186:189], v[208:211], v[34:37]
	v_mfma_f32_16x16x32_bf16 v[50:53], v[186:189], v[192:195], v[50:53]
	v_mfma_f32_16x16x32_bf16 v[50:53], v[234:237], v[204:207], v[50:53]
	v_mfma_f32_16x16x32_bf16 v[54:57], v[182:185], v[204:207], v[54:57]
	v_mfma_f32_16x16x32_bf16 v[54:57], v[178:181], v[192:195], v[54:57]
	s_barrier
	s_mov_b32 m0, s29
	ds_read_b128 v[142:145], v151
	global_load_lds_dwordx4 v130, s[24:25]
	s_mov_b32 m0, s30
	ds_read_b128 v[154:157], v151 offset:1024
	global_load_lds_dwordx4 v134, s[24:25]
	s_add_u32 s24, s24, 0x100000
	s_addc_u32 s25, s25, 0
	s_mov_b32 m0, s31
	ds_read_b128 v[158:161], v151 offset:2048
	global_load_lds_dwordx4 v130, s[24:25]
	s_mov_b32 m0, s33
	ds_read_b128 v[170:173], v151 offset:3072
	global_load_lds_dwordx4 v134, s[24:25]
	ds_read_b128 v[178:181], v152
	ds_read_b128 v[182:185], v152 offset:1024
	ds_read_b128 v[186:189], v152 offset:2048
	ds_read_b128 v[234:237], v152 offset:3072
	ds_read_b128 v[192:195], v150 offset:32768
	ds_read_b128 v[204:207], v150 offset:33792
	ds_read_b128 v[208:211], v150 offset:34816
	ds_read_b128 v[212:215], v150 offset:35840
	ds_read_b128 v[216:219], v150 offset:36864
	ds_read_b128 v[220:223], v150 offset:37888
	ds_read_b128 v[224:227], v150 offset:38912
	ds_read_b128 v[228:231], v150 offset:39936
	s_waitcnt vmcnt(8)
	s_waitcnt lgkmcnt(0)
	s_barrier
	v_mfma_f32_16x16x32_bf16 v[126:129], v[142:145], v[192:195], v[126:129]
	v_mfma_f32_16x16x32_bf16 v[126:129], v[154:157], v[204:207], v[126:129]
	v_mfma_f32_16x16x32_bf16 v[122:125], v[170:173], v[204:207], v[122:125]
	v_mfma_f32_16x16x32_bf16 v[122:125], v[158:161], v[192:195], v[122:125]
	v_mfma_f32_16x16x32_bf16 v[106:109], v[158:161], v[208:211], v[106:109]
	v_mfma_f32_16x16x32_bf16 v[106:109], v[170:173], v[212:215], v[106:109]
	v_mfma_f32_16x16x32_bf16 v[110:113], v[154:157], v[212:215], v[110:113]
	v_mfma_f32_16x16x32_bf16 v[110:113], v[142:145], v[208:211], v[110:113]
	v_mfma_f32_16x16x32_bf16 v[94:97], v[142:145], v[216:219], v[94:97]
	v_mfma_f32_16x16x32_bf16 v[94:97], v[154:157], v[220:223], v[94:97]
	v_mfma_f32_16x16x32_bf16 v[90:93], v[170:173], v[220:223], v[90:93]
	v_mfma_f32_16x16x32_bf16 v[90:93], v[158:161], v[216:219], v[90:93]
	v_mfma_f32_16x16x32_bf16 v[74:77], v[158:161], v[224:227], v[74:77]
	v_mfma_f32_16x16x32_bf16 v[74:77], v[170:173], v[228:231], v[74:77]
	v_mfma_f32_16x16x32_bf16 v[78:81], v[154:157], v[228:231], v[78:81]
	v_mfma_f32_16x16x32_bf16 v[78:81], v[142:145], v[224:227], v[78:81]
	v_mfma_f32_16x16x32_bf16 v[70:73], v[178:181], v[224:227], v[70:73]
	v_mfma_f32_16x16x32_bf16 v[70:73], v[182:185], v[228:231], v[70:73]
	v_mfma_f32_16x16x32_bf16 v[66:69], v[234:237], v[228:231], v[66:69]
	v_mfma_f32_16x16x32_bf16 v[66:69], v[186:189], v[224:227], v[66:69]
	v_mfma_f32_16x16x32_bf16 v[82:85], v[186:189], v[216:219], v[82:85]
	v_mfma_f32_16x16x32_bf16 v[82:85], v[234:237], v[220:223], v[82:85]
	v_mfma_f32_16x16x32_bf16 v[86:89], v[182:185], v[220:223], v[86:89]
	v_mfma_f32_16x16x32_bf16 v[86:89], v[178:181], v[216:219], v[86:89]
	v_mfma_f32_16x16x32_bf16 v[102:105], v[178:181], v[208:211], v[102:105]
	v_mfma_f32_16x16x32_bf16 v[102:105], v[182:185], v[212:215], v[102:105]
	v_mfma_f32_16x16x32_bf16 v[98:101], v[234:237], v[212:215], v[98:101]
	v_mfma_f32_16x16x32_bf16 v[98:101], v[186:189], v[208:211], v[98:101]
	v_mfma_f32_16x16x32_bf16 v[114:117], v[186:189], v[192:195], v[114:117]
	v_mfma_f32_16x16x32_bf16 v[114:117], v[234:237], v[204:207], v[114:117]
	v_mfma_f32_16x16x32_bf16 v[118:121], v[182:185], v[204:207], v[118:121]
	v_mfma_f32_16x16x32_bf16 v[118:121], v[178:181], v[192:195], v[118:121]
	s_barrier
	s_mov_b32 m0, s46
	s_add_u32 s22, s22, 0x80
	s_addc_u32 s23, s23, 0
	global_load_lds_dwordx4 v132, s[22:23]
	s_mov_b32 m0, s47
	ds_read_b128 v[192:195], v150 offset:49152
	global_load_lds_dwordx4 v136, s[22:23]
	s_mov_b32 m0, s48
	s_add_u32 s22, s22, 0x100000
	s_addc_u32 s23, s23, 0
	global_load_lds_dwordx4 v132, s[22:23]
	s_mov_b32 m0, s49
	ds_read_b128 v[204:207], v150 offset:50176
	global_load_lds_dwordx4 v136, s[22:23]
	ds_read_b128 v[208:211], v150 offset:51200
	ds_read_b128 v[212:215], v150 offset:52224
	ds_read_b128 v[216:219], v150 offset:53248
	ds_read_b128 v[220:223], v150 offset:54272
	ds_read_b128 v[224:227], v150 offset:55296
	ds_read_b128 v[228:231], v150 offset:56320
	s_waitcnt vmcnt(6)
	s_waitcnt lgkmcnt(0)
	s_barrier
	v_mfma_f32_16x16x32_bf16 v[62:65], v[142:145], v[192:195], v[62:65]
	v_mfma_f32_16x16x32_bf16 v[62:65], v[154:157], v[204:207], v[62:65]
	v_mfma_f32_16x16x32_bf16 v[58:61], v[170:173], v[204:207], v[58:61]
	v_mfma_f32_16x16x32_bf16 v[58:61], v[158:161], v[192:195], v[58:61]
	v_mfma_f32_16x16x32_bf16 v[42:45], v[158:161], v[208:211], v[42:45]
	v_mfma_f32_16x16x32_bf16 v[42:45], v[170:173], v[212:215], v[42:45]
	v_mfma_f32_16x16x32_bf16 v[46:49], v[154:157], v[212:215], v[46:49]
	v_mfma_f32_16x16x32_bf16 v[46:49], v[142:145], v[208:211], v[46:49]
	v_mfma_f32_16x16x32_bf16 v[30:33], v[142:145], v[216:219], v[30:33]
	v_mfma_f32_16x16x32_bf16 v[30:33], v[154:157], v[220:223], v[30:33]
	v_mfma_f32_16x16x32_bf16 v[26:29], v[170:173], v[220:223], v[26:29]
	v_mfma_f32_16x16x32_bf16 v[26:29], v[158:161], v[216:219], v[26:29]
	v_mfma_f32_16x16x32_bf16 v[10:13], v[158:161], v[224:227], v[10:13]
	v_mfma_f32_16x16x32_bf16 v[10:13], v[170:173], v[228:231], v[10:13]
	v_mfma_f32_16x16x32_bf16 v[14:17], v[154:157], v[228:231], v[14:17]
	v_mfma_f32_16x16x32_bf16 v[14:17], v[142:145], v[224:227], v[14:17]
	v_mfma_f32_16x16x32_bf16 v[6:9], v[178:181], v[224:227], v[6:9]
	v_mfma_f32_16x16x32_bf16 v[6:9], v[182:185], v[228:231], v[6:9]
	v_mfma_f32_16x16x32_bf16 v[2:5], v[234:237], v[228:231], v[2:5]
	v_mfma_f32_16x16x32_bf16 v[2:5], v[186:189], v[224:227], v[2:5]
	v_mfma_f32_16x16x32_bf16 v[18:21], v[186:189], v[216:219], v[18:21]
	v_mfma_f32_16x16x32_bf16 v[18:21], v[234:237], v[220:223], v[18:21]
	v_mfma_f32_16x16x32_bf16 v[22:25], v[182:185], v[220:223], v[22:25]
	v_mfma_f32_16x16x32_bf16 v[22:25], v[178:181], v[216:219], v[22:25]
	v_mfma_f32_16x16x32_bf16 v[38:41], v[178:181], v[208:211], v[38:41]
	v_mfma_f32_16x16x32_bf16 v[38:41], v[182:185], v[212:215], v[38:41]
	v_mfma_f32_16x16x32_bf16 v[34:37], v[234:237], v[212:215], v[34:37]
	v_mfma_f32_16x16x32_bf16 v[34:37], v[186:189], v[208:211], v[34:37]
	v_mfma_f32_16x16x32_bf16 v[50:53], v[186:189], v[192:195], v[50:53]
	v_mfma_f32_16x16x32_bf16 v[50:53], v[234:237], v[204:207], v[50:53]
	v_mfma_f32_16x16x32_bf16 v[54:57], v[182:185], v[204:207], v[54:57]
	v_mfma_f32_16x16x32_bf16 v[54:57], v[178:181], v[192:195], v[54:57]
	s_barrier
	s_add_i32 s57, s57, 2
	s_add_u32 s20, s20, 0x100
	s_addc_u32 s21, s21, 0
	s_add_u32 s55, s55, 0x100
	s_addc_u32 s56, s56, 0
	s_cmp_gt_u32 s57, 61
	s_cbranch_scc0 .LBB0_2373
	s_and_b64 vcc, exec, s[16:17]
	s_cbranch_vccz .LBB0_2376
	s_barrier
